# adds trimmed topk score tail (saddr store, 3-op order key, no vcc) on top of v47 stack
# speedup vs baseline: 1.0133x; 1.0017x over previous
.LBB0_703:
	s_mov_b32 s94, 0x7fff0000
	s_mov_b32 s95, 0x7fff0000
	s_mov_b32 s97, 0
	v_lshlrev_b32_e32 v238, 2, v121

.Ltk_e_go:
	v_med3_f32 v194, v194, 0, v125
	v_mfma_f32_32x32x16_bf16 v[2:17], v[58:61], v[162:165], 0
	v_fma_f32 v226, v91, v194, 0
	v_med3_f32 v195, v195, 0, v125
	v_fma_f32 v227, v93, v195, 0
	v_med3_f32 v196, v196, 0, v125
	v_fmac_f32_e32 v226, v95, v196
	v_med3_f32 v197, v197, 0, v125
	v_fmac_f32_e32 v227, v129, v197
	v_mfma_f32_32x32x16_bf16 v[18:33], v[74:77], v[162:165], 0
	v_med3_f32 v198, v198, 0, v125
	v_fmac_f32_e32 v226, v130, v198
	v_med3_f32 v199, v199, 0, v125
	v_fmac_f32_e32 v227, v131, v199
	v_med3_f32 v200, v200, 0, v125
	v_fmac_f32_e32 v226, v132, v200
	v_med3_f32 v201, v201, 0, v125
	v_mfma_f32_32x32x16_bf16 v[2:17], v[50:53], v[166:169], v[2:17]
	v_fmac_f32_e32 v227, v133, v201
	v_med3_f32 v202, v202, 0, v125
	v_fmac_f32_e32 v226, v134, v202
	v_med3_f32 v203, v203, 0, v125
	v_fmac_f32_e32 v227, v135, v203
	v_med3_f32 v204, v204, 0, v125
	v_fmac_f32_e32 v226, v136, v204
	v_mfma_f32_32x32x16_bf16 v[18:33], v[66:69], v[166:169], v[18:33]
	v_med3_f32 v205, v205, 0, v125
	v_fmac_f32_e32 v227, v137, v205
	v_med3_f32 v206, v206, 0, v125
	v_fmac_f32_e32 v226, v138, v206
	v_med3_f32 v207, v207, 0, v125
	v_fmac_f32_e32 v227, v139, v207
	v_med3_f32 v208, v208, 0, v125
	v_mfma_f32_32x32x16_bf16 v[2:17], v[54:57], v[170:173], v[2:17]
	v_fmac_f32_e32 v226, v140, v208
	v_med3_f32 v209, v209, 0, v125
	v_fmac_f32_e32 v227, v141, v209
	v_add_f32_e32 v228, v227, v226
	v_med3_f32 v210, v210, 0, v125
	v_fma_f32 v229, v142, v210, 0
	v_med3_f32 v211, v211, 0, v125
	v_mfma_f32_32x32x16_bf16 v[18:33], v[70:73], v[170:173], v[18:33]
	v_fma_f32 v230, v143, v211, 0
	v_med3_f32 v212, v212, 0, v125
	v_fmac_f32_e32 v229, v144, v212
	v_med3_f32 v213, v213, 0, v125
	v_fmac_f32_e32 v230, v145, v213
	v_med3_f32 v214, v214, 0, v125
	v_fmac_f32_e32 v229, v146, v214
	v_mfma_f32_32x32x16_bf16 v[2:17], v[62:65], v[174:177], v[2:17]
	v_med3_f32 v215, v215, 0, v125
	v_fmac_f32_e32 v230, v147, v215
	v_med3_f32 v216, v216, 0, v125
	v_fmac_f32_e32 v229, v148, v216
	v_med3_f32 v217, v217, 0, v125
	v_fmac_f32_e32 v230, v149, v217
	v_med3_f32 v218, v218, 0, v125
	v_mfma_f32_32x32x16_bf16 v[18:33], v[78:81], v[174:177], v[18:33]
	v_fmac_f32_e32 v229, v150, v218
	v_med3_f32 v219, v219, 0, v125
	v_fmac_f32_e32 v230, v151, v219
	v_med3_f32 v220, v220, 0, v125
	v_fmac_f32_e32 v229, v152, v220
	v_med3_f32 v221, v221, 0, v125
	v_fmac_f32_e32 v230, v153, v221
	v_med3_f32 v222, v222, 0, v125
	v_fmac_f32_e32 v229, v154, v222
	v_med3_f32 v223, v223, 0, v125
	v_fmac_f32_e32 v230, v155, v223
	v_med3_f32 v224, v224, 0, v125
	v_fmac_f32_e32 v229, v156, v224
	v_med3_f32 v225, v225, 0, v125
	v_fmac_f32_e32 v230, v157, v225
	v_add_f32_e32 v231, v230, v229
	s_lshl_b32 s16, s95, 2
	s_add_u32 s68, s36, s16
	s_addc_u32 s69, s37, 0
	s_sub_i32 s96, s22, s95
	v_permlane32_swap_b32_e32 v228, v231
	v_add_f32_e32 v232, v228, v231
	v_cmp_gt_i32_e32 vcc, s96, v100
	s_and_saveexec_b64 s[18:19], vcc
	global_store_dword v238, v232, s[68:69]
	v_ashrrev_i32_e32 v233, 31, v232
	v_or_b32_e32 v233, 0x80000000, v233
	v_xor_b32_e32 v233, v232, v233
	v_bfe_u32 v233, v233, 22, 10
	v_lshl_add_u32 v233, v233, 2, v119
	ds_add_u32 v233, v124
	s_or_b64 exec, exec, s[18:19]
	s_mov_b32 s94, s33
	s_add_i32 s16, s33, 32
	s_cmp_gt_i32 s16, s23
	s_cbranch_scc1 .Ltk_drain_e
	s_add_i32 s17, s33, 64
	s_cmpk_eq_i32 s31, 0xc0
	s_cbranch_scc1 .Ltk_o_nob0
	s_cmp_gt_i32 s17, s23
	s_cbranch_scc1 .Ltk_o_nob0
	ds_read_b128 v[162:165], v160 offset:9216
	ds_read_b128 v[166:169], v160 offset:9248
	ds_read_b128 v[170:173], v160 offset:9280
	ds_read_b128 v[174:177], v160 offset:9312
	s_waitcnt lgkmcnt(4)
	s_branch .Ltk_o_go

.Ltk_o_go:
	v_med3_f32 v2, v2, 0, v125
	v_mfma_f32_32x32x16_bf16 v[194:209], v[58:61], v[178:181], 0
	v_fma_f32 v226, v91, v2, 0
	v_med3_f32 v3, v3, 0, v125
	v_fma_f32 v227, v93, v3, 0
	v_med3_f32 v4, v4, 0, v125
	v_fmac_f32_e32 v226, v95, v4
	v_med3_f32 v5, v5, 0, v125
	v_fmac_f32_e32 v227, v129, v5
	v_mfma_f32_32x32x16_bf16 v[210:225], v[74:77], v[178:181], 0
	v_med3_f32 v6, v6, 0, v125
	v_fmac_f32_e32 v226, v130, v6
	v_med3_f32 v7, v7, 0, v125
	v_fmac_f32_e32 v227, v131, v7
	v_med3_f32 v8, v8, 0, v125
	v_fmac_f32_e32 v226, v132, v8
	v_med3_f32 v9, v9, 0, v125
	v_mfma_f32_32x32x16_bf16 v[194:209], v[50:53], v[182:185], v[194:209]
	v_fmac_f32_e32 v227, v133, v9
	v_med3_f32 v10, v10, 0, v125
	v_fmac_f32_e32 v226, v134, v10
	v_med3_f32 v11, v11, 0, v125
	v_fmac_f32_e32 v227, v135, v11
	v_med3_f32 v12, v12, 0, v125
	v_fmac_f32_e32 v226, v136, v12
	v_mfma_f32_32x32x16_bf16 v[210:225], v[66:69], v[182:185], v[210:225]
	v_med3_f32 v13, v13, 0, v125
	v_fmac_f32_e32 v227, v137, v13
	v_med3_f32 v14, v14, 0, v125
	v_fmac_f32_e32 v226, v138, v14
	v_med3_f32 v15, v15, 0, v125
	v_fmac_f32_e32 v227, v139, v15
	v_med3_f32 v16, v16, 0, v125
	v_mfma_f32_32x32x16_bf16 v[194:209], v[54:57], v[186:189], v[194:209]
	v_fmac_f32_e32 v226, v140, v16
	v_med3_f32 v17, v17, 0, v125
	v_fmac_f32_e32 v227, v141, v17
	v_add_f32_e32 v228, v227, v226
	v_med3_f32 v18, v18, 0, v125
	v_fma_f32 v229, v142, v18, 0
	v_med3_f32 v19, v19, 0, v125
	v_mfma_f32_32x32x16_bf16 v[210:225], v[70:73], v[186:189], v[210:225]
	v_fma_f32 v230, v143, v19, 0
	v_med3_f32 v20, v20, 0, v125
	v_fmac_f32_e32 v229, v144, v20
	v_med3_f32 v21, v21, 0, v125
	v_fmac_f32_e32 v230, v145, v21
	v_med3_f32 v22, v22, 0, v125
	v_fmac_f32_e32 v229, v146, v22
	v_mfma_f32_32x32x16_bf16 v[194:209], v[62:65], v[190:193], v[194:209]
	v_med3_f32 v23, v23, 0, v125
	v_fmac_f32_e32 v230, v147, v23
	v_med3_f32 v24, v24, 0, v125
	v_fmac_f32_e32 v229, v148, v24
	v_med3_f32 v25, v25, 0, v125
	v_fmac_f32_e32 v230, v149, v25
	v_med3_f32 v26, v26, 0, v125
	v_mfma_f32_32x32x16_bf16 v[210:225], v[78:81], v[190:193], v[210:225]
	v_fmac_f32_e32 v229, v150, v26
	v_med3_f32 v27, v27, 0, v125
	v_fmac_f32_e32 v230, v151, v27
	v_med3_f32 v28, v28, 0, v125
	v_fmac_f32_e32 v229, v152, v28
	v_med3_f32 v29, v29, 0, v125
	v_fmac_f32_e32 v230, v153, v29
	v_med3_f32 v30, v30, 0, v125
	v_fmac_f32_e32 v229, v154, v30
	v_med3_f32 v31, v31, 0, v125
	v_fmac_f32_e32 v230, v155, v31
	v_med3_f32 v32, v32, 0, v125
	v_fmac_f32_e32 v229, v156, v32
	v_med3_f32 v33, v33, 0, v125
	v_fmac_f32_e32 v230, v157, v33
	v_add_f32_e32 v231, v230, v229
	s_lshl_b32 s16, s94, 2
	s_add_u32 s68, s36, s16
	s_addc_u32 s69, s37, 0
	s_sub_i32 s96, s22, s94
	v_permlane32_swap_b32_e32 v228, v231
	v_add_f32_e32 v232, v228, v231
	v_cmp_gt_i32_e32 vcc, s96, v100
	s_and_saveexec_b64 s[18:19], vcc
	global_store_dword v238, v232, s[68:69]
	v_ashrrev_i32_e32 v233, 31, v232
	v_or_b32_e32 v233, 0x80000000, v233
	v_xor_b32_e32 v233, v232, v233
	v_bfe_u32 v233, v233, 22, 10
	v_lshl_add_u32 v233, v233, 2, v119
	ds_add_u32 v233, v124
	s_or_b64 exec, exec, s[18:19]
	s_add_i32 s95, s33, 32
	s_add_i32 s17, s33, 64
	s_cmp_gt_i32 s17, s23
	s_cbranch_scc1 .Ltk_drain_o
	s_cmpk_eq_i32 s31, 0xc0
	s_cbranch_scc1 .Ltk_blockend
	s_add_i32 s31, s31, 64
	v_add_u32_e32 v160, 0x2400, v160
	s_branch .Ltk_pair

.Ltk_drain_e:
	v_med3_f32 v2, v2, 0, v125
	v_fma_f32 v226, v91, v2, 0
	v_med3_f32 v3, v3, 0, v125
	v_fma_f32 v227, v93, v3, 0
	v_med3_f32 v4, v4, 0, v125
	v_fmac_f32_e32 v226, v95, v4
	v_med3_f32 v5, v5, 0, v125
	v_fmac_f32_e32 v227, v129, v5
	v_med3_f32 v6, v6, 0, v125
	v_fmac_f32_e32 v226, v130, v6
	v_med3_f32 v7, v7, 0, v125
	v_fmac_f32_e32 v227, v131, v7
	v_med3_f32 v8, v8, 0, v125
	v_fmac_f32_e32 v226, v132, v8
	v_med3_f32 v9, v9, 0, v125
	v_fmac_f32_e32 v227, v133, v9
	v_med3_f32 v10, v10, 0, v125
	v_fmac_f32_e32 v226, v134, v10
	v_med3_f32 v11, v11, 0, v125
	v_fmac_f32_e32 v227, v135, v11
	v_med3_f32 v12, v12, 0, v125
	v_fmac_f32_e32 v226, v136, v12
	v_med3_f32 v13, v13, 0, v125
	v_fmac_f32_e32 v227, v137, v13
	v_med3_f32 v14, v14, 0, v125
	v_fmac_f32_e32 v226, v138, v14
	v_med3_f32 v15, v15, 0, v125
	v_fmac_f32_e32 v227, v139, v15
	v_med3_f32 v16, v16, 0, v125
	v_fmac_f32_e32 v226, v140, v16
	v_med3_f32 v17, v17, 0, v125
	v_fmac_f32_e32 v227, v141, v17
	v_add_f32_e32 v228, v227, v226
	v_med3_f32 v18, v18, 0, v125
	v_fma_f32 v229, v142, v18, 0
	v_med3_f32 v19, v19, 0, v125
	v_fma_f32 v230, v143, v19, 0
	v_med3_f32 v20, v20, 0, v125
	v_fmac_f32_e32 v229, v144, v20
	v_med3_f32 v21, v21, 0, v125
	v_fmac_f32_e32 v230, v145, v21
	v_med3_f32 v22, v22, 0, v125
	v_fmac_f32_e32 v229, v146, v22
	v_med3_f32 v23, v23, 0, v125
	v_fmac_f32_e32 v230, v147, v23
	v_med3_f32 v24, v24, 0, v125
	v_fmac_f32_e32 v229, v148, v24
	v_med3_f32 v25, v25, 0, v125
	v_fmac_f32_e32 v230, v149, v25
	v_med3_f32 v26, v26, 0, v125
	v_fmac_f32_e32 v229, v150, v26
	v_med3_f32 v27, v27, 0, v125
	v_fmac_f32_e32 v230, v151, v27
	v_med3_f32 v28, v28, 0, v125
	v_fmac_f32_e32 v229, v152, v28
	v_med3_f32 v29, v29, 0, v125
	v_fmac_f32_e32 v230, v153, v29
	v_med3_f32 v30, v30, 0, v125
	v_fmac_f32_e32 v229, v154, v30
	v_med3_f32 v31, v31, 0, v125
	v_fmac_f32_e32 v230, v155, v31
	v_med3_f32 v32, v32, 0, v125
	v_fmac_f32_e32 v229, v156, v32
	v_med3_f32 v33, v33, 0, v125
	v_fmac_f32_e32 v230, v157, v33
	v_add_f32_e32 v231, v230, v229
	s_lshl_b32 s16, s94, 2
	s_add_u32 s68, s36, s16
	s_addc_u32 s69, s37, 0
	s_sub_i32 s96, s22, s94
	v_permlane32_swap_b32_e32 v228, v231
	v_add_f32_e32 v232, v228, v231
	v_cmp_gt_i32_e32 vcc, s96, v100
	s_and_saveexec_b64 s[18:19], vcc
	global_store_dword v238, v232, s[68:69]
	v_ashrrev_i32_e32 v233, 31, v232
	v_or_b32_e32 v233, 0x80000000, v233
	v_xor_b32_e32 v233, v232, v233
	v_bfe_u32 v233, v233, 22, 10
	v_lshl_add_u32 v233, v233, 2, v119
	ds_add_u32 v233, v124
	s_or_b64 exec, exec, s[18:19]
	s_branch .Ltk_done
.Ltk_drain_o:
	v_med3_f32 v194, v194, 0, v125
	v_fma_f32 v226, v91, v194, 0
	v_med3_f32 v195, v195, 0, v125
	v_fma_f32 v227, v93, v195, 0
	v_med3_f32 v196, v196, 0, v125
	v_fmac_f32_e32 v226, v95, v196
	v_med3_f32 v197, v197, 0, v125
	v_fmac_f32_e32 v227, v129, v197
	v_med3_f32 v198, v198, 0, v125
	v_fmac_f32_e32 v226, v130, v198
	v_med3_f32 v199, v199, 0, v125
	v_fmac_f32_e32 v227, v131, v199
	v_med3_f32 v200, v200, 0, v125
	v_fmac_f32_e32 v226, v132, v200
	v_med3_f32 v201, v201, 0, v125
	v_fmac_f32_e32 v227, v133, v201
	v_med3_f32 v202, v202, 0, v125
	v_fmac_f32_e32 v226, v134, v202
	v_med3_f32 v203, v203, 0, v125
	v_fmac_f32_e32 v227, v135, v203
	v_med3_f32 v204, v204, 0, v125
	v_fmac_f32_e32 v226, v136, v204
	v_med3_f32 v205, v205, 0, v125
	v_fmac_f32_e32 v227, v137, v205
	v_med3_f32 v206, v206, 0, v125
	v_fmac_f32_e32 v226, v138, v206
	v_med3_f32 v207, v207, 0, v125
	v_fmac_f32_e32 v227, v139, v207
	v_med3_f32 v208, v208, 0, v125
	v_fmac_f32_e32 v226, v140, v208
	v_med3_f32 v209, v209, 0, v125
	v_fmac_f32_e32 v227, v141, v209
	v_add_f32_e32 v228, v227, v226
	v_med3_f32 v210, v210, 0, v125
	v_fma_f32 v229, v142, v210, 0
	v_med3_f32 v211, v211, 0, v125
	v_fma_f32 v230, v143, v211, 0
	v_med3_f32 v212, v212, 0, v125
	v_fmac_f32_e32 v229, v144, v212
	v_med3_f32 v213, v213, 0, v125
	v_fmac_f32_e32 v230, v145, v213
	v_med3_f32 v214, v214, 0, v125
	v_fmac_f32_e32 v229, v146, v214
	v_med3_f32 v215, v215, 0, v125
	v_fmac_f32_e32 v230, v147, v215
	v_med3_f32 v216, v216, 0, v125
	v_fmac_f32_e32 v229, v148, v216
	v_med3_f32 v217, v217, 0, v125
	v_fmac_f32_e32 v230, v149, v217
	v_med3_f32 v218, v218, 0, v125
	v_fmac_f32_e32 v229, v150, v218
	v_med3_f32 v219, v219, 0, v125
	v_fmac_f32_e32 v230, v151, v219
	v_med3_f32 v220, v220, 0, v125
	v_fmac_f32_e32 v229, v152, v220
	v_med3_f32 v221, v221, 0, v125
	v_fmac_f32_e32 v230, v153, v221
	v_med3_f32 v222, v222, 0, v125
	v_fmac_f32_e32 v229, v154, v222
	v_med3_f32 v223, v223, 0, v125
	v_fmac_f32_e32 v230, v155, v223
	v_med3_f32 v224, v224, 0, v125
	v_fmac_f32_e32 v229, v156, v224
	v_med3_f32 v225, v225, 0, v125
	v_fmac_f32_e32 v230, v157, v225
	v_add_f32_e32 v231, v230, v229
	s_lshl_b32 s16, s95, 2
	s_add_u32 s68, s36, s16
	s_addc_u32 s69, s37, 0
	s_sub_i32 s96, s22, s95
	v_permlane32_swap_b32_e32 v228, v231
	v_add_f32_e32 v232, v228, v231
	v_cmp_gt_i32_e32 vcc, s96, v100
	s_and_saveexec_b64 s[18:19], vcc
	global_store_dword v238, v232, s[68:69]
	v_ashrrev_i32_e32 v233, 31, v232
	v_or_b32_e32 v233, 0x80000000, v233
	v_xor_b32_e32 v233, v232, v233
	v_bfe_u32 v233, v233, 22, 10
	v_lshl_add_u32 v233, v233, 2, v119
	ds_add_u32 v233, v124
	s_or_b64 exec, exec, s[18:19]
